# a9 + local-barrier leader issues its release atomic last and does not wait for it
# speedup vs baseline: 1.0031x; 1.0031x over previous
.LBB0_411:
	s_andn2_saveexec_b64 s[6:7], s[6:7]
	s_cbranch_execz .LBB0_431
	s_mov_b64 s[6:7], exec
	v_mov_b32_e32 v1, 0x20008
	ds_read_b32 v1, v1
	s_waitcnt lgkmcnt(0)
	s_nop 0
	v_readfirstlane_b32 s32, v1
	s_nop 3
	s_cmp_eq_u32 s32, 0
	s_cbranch_scc1 .Lmy_fullbar_0
	v_mov_b32_e32 v1, 0x2000
	v_mov_b32_e32 v3, 1
	buffer_inv sc1
	s_waitcnt vmcnt(0)
	global_atomic_add v1, v3, s[4:5] offset:1024
	s_branch .LBB0_431

.LBB0_785:
	s_andn2_saveexec_b64 s[8:9], s[18:19]
	s_cbranch_execz .LBB0_805
	s_mov_b64 s[18:19], exec
	v_mov_b32_e32 v1, 0x20008
	ds_read_b32 v1, v1
	s_waitcnt lgkmcnt(0)
	s_nop 0
	v_readfirstlane_b32 s32, v1
	s_nop 3
	s_cmp_eq_u32 s32, 0
	s_cbranch_scc1 .Lmy_fullbar_2
	v_mov_b32_e32 v1, 0x2000
	v_mov_b32_e32 v3, 1
	buffer_inv sc1
	s_waitcnt vmcnt(0)
	global_atomic_add v1, v3, s[16:17] offset:1024
	s_branch .LBB0_805

.LBB0_842:
	s_andn2_saveexec_b64 s[8:9], s[20:21]
	s_cbranch_execz .LBB0_862
	s_mov_b64 s[20:21], exec
	v_mov_b32_e32 v1, 0x20008
	ds_read_b32 v1, v1
	s_waitcnt lgkmcnt(0)
	s_nop 0
	v_readfirstlane_b32 s32, v1
	s_nop 3
	s_cmp_eq_u32 s32, 0
	s_cbranch_scc1 .Lmy_fullbar_3
	v_mov_b32_e32 v1, 0x2000
	v_mov_b32_e32 v3, 1
	buffer_inv sc1
	s_waitcnt vmcnt(0)
	global_atomic_add v1, v3, s[16:17] offset:1024
	s_branch .LBB0_862

.LBB0_1003:
	s_andn2_saveexec_b64 s[8:9], s[20:21]
	s_cbranch_execz .LBB0_1023
	s_mov_b64 s[20:21], exec
	v_mov_b32_e32 v1, 0x20008
	ds_read_b32 v1, v1
	s_waitcnt lgkmcnt(0)
	s_nop 0
	v_readfirstlane_b32 s32, v1
	s_nop 3
	s_cmp_eq_u32 s32, 0
	s_cbranch_scc1 .Lmy_fullbar_4
	v_mov_b32_e32 v1, 0x2000
	v_mov_b32_e32 v3, 1
	buffer_inv sc1
	s_waitcnt vmcnt(0)
	global_atomic_add v1, v3, s[6:7] offset:1024
	s_branch .LBB0_1023

.LBB0_1111:
	s_andn2_saveexec_b64 s[8:9], s[14:15]
	s_cbranch_execz .LBB0_1131
	s_mov_b64 s[14:15], exec
	v_mov_b32_e32 v1, 0x20008
	ds_read_b32 v1, v1
	s_waitcnt lgkmcnt(0)
	s_nop 0
	v_readfirstlane_b32 s32, v1
	s_nop 3
	s_cmp_eq_u32 s32, 0
	s_cbranch_scc1 .Lmy_fullbar_5
	v_mov_b32_e32 v1, 0x2000
	v_mov_b32_e32 v3, 1
	buffer_inv sc1
	s_waitcnt vmcnt(0)
	global_atomic_add v1, v3, s[6:7] offset:1024
	s_branch .LBB0_1131

.LBB0_1205:
	s_andn2_saveexec_b64 s[8:9], s[16:17]
	s_cbranch_execz .LBB0_1225
	s_mov_b64 s[16:17], exec
	v_mov_b32_e32 v1, 0x20008
	ds_read_b32 v1, v1
	s_waitcnt lgkmcnt(0)
	s_nop 0
	v_readfirstlane_b32 s32, v1
	s_nop 3
	s_cmp_eq_u32 s32, 0
	s_cbranch_scc1 .Lmy_fullbar_6
	v_mov_b32_e32 v1, 0x2000
	v_mov_b32_e32 v3, 1
	buffer_inv sc1
	s_waitcnt vmcnt(0)
	global_atomic_add v1, v3, s[6:7] offset:1024
	s_branch .LBB0_1225

.LBB0_1273:
	s_andn2_saveexec_b64 s[8:9], s[8:9]
	s_cbranch_execz .LBB0_1293
	s_mov_b64 s[8:9], exec
	v_mov_b32_e32 v1, 0x20008
	ds_read_b32 v1, v1
	s_waitcnt lgkmcnt(0)
	s_nop 0
	v_readfirstlane_b32 s32, v1
	s_nop 3
	s_cmp_eq_u32 s32, 0
	s_cbranch_scc1 .Lmy_fullbar_7
	v_mov_b32_e32 v1, 0x2000
	v_mov_b32_e32 v3, 1
	buffer_inv sc1
	s_waitcnt vmcnt(0)
	global_atomic_add v1, v3, s[6:7] offset:1024
	s_branch .LBB0_1293
